# EpiResid epilogues (down + out GEMM): residual-row loads of row blocks 1..7 issued up front instead of one load per vmcnt wait
# speedup vs baseline: 1.0218x; 1.0001x over previous
.LBB0_56:
	v_lshl_add_u32 v146, s48, 8, v162
	v_lshl_or_b32 v144, s56, 5, v149
	v_ashrrev_i32_e32 v147, 31, v146
	v_lshl_or_b32 v144, s14, 8, v144
	v_lshlrev_b64 v[154:155], 11, v[146:147]
	v_lshl_add_u64 v[154:155], s[18:19], 0, v[154:155]
	v_ashrrev_i32_e32 v145, 31, v144
	v_lshl_add_u64 v[154:155], v[144:145], 1, v[154:155]
	global_load_dwordx4 v[168:171], v[154:155], off
	v_add_co_u32_e32 v188, vcc, 0x8000, v154
	s_nop 1
	v_addc_co_u32_e32 v189, vcc, 0, v155, vcc
	global_load_dwordx4 v[174:177], v[188:189], off
	global_load_dwordx4 v[178:181], v[188:189], off offset:256
	v_add_co_u32_e32 v188, vcc, 0x10000, v154
	s_nop 1
	v_addc_co_u32_e32 v189, vcc, 0, v155, vcc
	global_load_dwordx4 v[182:185], v[188:189], off
	global_load_dwordx4 v[208:211], v[188:189], off offset:256
	v_add_co_u32_e32 v188, vcc, 0x18000, v154
	s_nop 1
	v_addc_co_u32_e32 v189, vcc, 0, v155, vcc
	global_load_dwordx4 v[212:215], v[188:189], off
	global_load_dwordx4 v[216:219], v[188:189], off offset:256
	v_add_co_u32_e32 v188, vcc, 0x40000, v154
	s_nop 1
	v_addc_co_u32_e32 v189, vcc, 0, v155, vcc
	global_load_dwordx4 v[220:223], v[188:189], off
	global_load_dwordx4 v[224:227], v[188:189], off offset:256
	v_add_co_u32_e32 v188, vcc, 0x48000, v154
	s_nop 1
	v_addc_co_u32_e32 v189, vcc, 0, v155, vcc
	global_load_dwordx4 v[228:231], v[188:189], off
	global_load_dwordx4 v[232:235], v[188:189], off offset:256
	v_add_co_u32_e32 v188, vcc, 0x50000, v154
	s_nop 1
	v_addc_co_u32_e32 v189, vcc, 0, v155, vcc
	global_load_dwordx4 v[236:239], v[188:189], off
	global_load_dwordx4 v[240:243], v[188:189], off offset:256
	v_add_co_u32_e32 v188, vcc, 0x58000, v154
	s_nop 1
	v_addc_co_u32_e32 v189, vcc, 0, v155, vcc
	global_load_dwordx4 v[244:247], v[188:189], off
	global_load_dwordx4 v[248:251], v[188:189], off offset:256
	s_lshl_b32 s14, s14, 2
	s_ashr_i32 s15, s14, 31
	s_waitcnt vmcnt(14)
	v_lshlrev_b32_e32 v156, 16, v168
	v_and_b32_e32 v157, 0xffff0000, v168
	v_lshlrev_b32_e32 v168, 16, v169
	v_and_b32_e32 v169, 0xffff0000, v169
	v_lshlrev_b32_e32 v172, 16, v170
	v_and_b32_e32 v173, 0xffff0000, v170
	v_lshlrev_b32_e32 v170, 16, v171
	v_and_b32_e32 v171, 0xffff0000, v171
	v_pk_add_f32 v[168:169], v[128:129], v[168:169]
	v_pk_add_f32 v[156:157], v[126:127], v[156:157]
	v_pk_add_f32 v[170:171], v[124:125], v[170:171]
	v_pk_add_f32 v[172:173], v[122:123], v[172:173]
	v_cvt_pk_bf16_f32 v122, v156, v157
	v_cvt_pk_bf16_f32 v123, v168, v169
	v_mul_f32_e32 v157, v157, v157
	v_cvt_pk_bf16_f32 v124, v172, v173
	v_cvt_pk_bf16_f32 v125, v170, v171
	global_load_dwordx4 v[126:129], v[154:155], off offset:256
	v_mul_f32_e32 v167, v169, v169
	v_mul_f32_e32 v169, v173, v173
	v_fmac_f32_e32 v157, v156, v156
	v_fmac_f32_e32 v167, v168, v168
	v_mul_f32_e32 v171, v171, v171
	v_fmac_f32_e32 v169, v172, v172
	v_add_f32_e32 v156, v157, v167
	v_fmac_f32_e32 v171, v170, v170
	v_add_f32_e32 v156, v169, v156
	v_add_f32_e32 v167, v171, v156
	global_store_dwordx4 v[154:155], v[122:125], off
	s_waitcnt vmcnt(1)
	v_lshlrev_b32_e32 v156, 16, v126
	v_and_b32_e32 v157, 0xffff0000, v126
	v_lshlrev_b32_e32 v126, 16, v127
	v_and_b32_e32 v127, 0xffff0000, v127
	v_lshlrev_b32_e32 v168, 16, v128
	v_and_b32_e32 v169, 0xffff0000, v128
	v_lshlrev_b32_e32 v128, 16, v129
	v_and_b32_e32 v129, 0xffff0000, v129
	v_pk_add_f32 v[120:121], v[120:121], v[126:127]
	v_pk_add_f32 v[118:119], v[118:119], v[156:157]
	v_pk_add_f32 v[126:127], v[116:117], v[128:129]
	v_pk_add_f32 v[128:129], v[114:115], v[168:169]
	v_mul_f32_e32 v114, v119, v119
	v_mul_f32_e32 v115, v121, v121
	v_mul_f32_e32 v116, v129, v129
	v_fmac_f32_e32 v114, v118, v118
	v_fmac_f32_e32 v115, v120, v120
	v_mul_f32_e32 v117, v127, v127
	v_fmac_f32_e32 v116, v128, v128
	v_add_f32_e32 v114, v114, v115
	v_add_f32_e32 v114, v116, v114
	v_fmac_f32_e32 v117, v126, v126
	v_add_f32_e32 v114, v117, v114
	v_add_f32_e32 v114, v167, v114
	ds_bpermute_b32 v115, v164, v114
	v_cvt_pk_bf16_f32 v116, v118, v119
	v_cvt_pk_bf16_f32 v117, v120, v121
	v_cvt_pk_bf16_f32 v118, v128, v129
	v_cvt_pk_bf16_f32 v119, v126, v127
	s_waitcnt lgkmcnt(0)
	v_add_f32_e32 v114, v114, v115
	ds_bpermute_b32 v115, v165, v114
	global_store_dwordx4 v[154:155], v[116:119], off offset:256
	s_and_saveexec_b64 s[48:49], s[38:39]
	s_cbranch_execz .LBB0_58
	v_lshlrev_b64 v[116:117], 6, v[146:147]
	v_lshl_add_u64 v[116:117], s[78:79], 0, v[116:117]
	v_lshl_add_u64 v[116:117], s[14:15], 2, v[116:117]
	s_lshl_b32 s24, s56, 2
	v_lshl_add_u64 v[116:117], v[116:117], 0, s[24:25]
	s_waitcnt lgkmcnt(0)
	v_add_f32_e32 v114, v114, v115
	global_store_dword v[116:117], v114, off
.LBB0_58:
	s_or_b64 exec, exec, s[48:49]
	v_or_b32_e32 v114, 16, v146
	s_waitcnt lgkmcnt(0)
	v_ashrrev_i32_e32 v115, 31, v114
	v_lshlrev_b64 v[116:117], 11, v[114:115]
	v_lshl_add_u64 v[116:117], s[18:19], 0, v[116:117]
	v_lshl_add_u64 v[120:121], v[144:145], 1, v[116:117]
	v_mov_b32_e32 v116, v174
	v_mov_b32_e32 v117, v175
	v_mov_b32_e32 v118, v176
	v_mov_b32_e32 v119, v177
	v_lshlrev_b32_e32 v122, 16, v116
	v_and_b32_e32 v123, 0xffff0000, v116
	v_lshlrev_b32_e32 v116, 16, v117
	v_and_b32_e32 v117, 0xffff0000, v117
	v_lshlrev_b32_e32 v124, 16, v118
	v_and_b32_e32 v125, 0xffff0000, v118
	v_lshlrev_b32_e32 v118, 16, v119
	v_and_b32_e32 v119, 0xffff0000, v119
	v_pk_add_f32 v[116:117], v[112:113], v[116:117]
	v_pk_add_f32 v[122:123], v[110:111], v[122:123]
	v_pk_add_f32 v[118:119], v[108:109], v[118:119]
	v_pk_add_f32 v[124:125], v[106:107], v[124:125]
	v_cvt_pk_bf16_f32 v106, v122, v123
	v_cvt_pk_bf16_f32 v107, v116, v117
	v_mul_f32_e32 v123, v123, v123
	v_cvt_pk_bf16_f32 v108, v124, v125
	v_cvt_pk_bf16_f32 v109, v118, v119
	v_mov_b32_e32 v110, v178
	v_mov_b32_e32 v111, v179
	v_mov_b32_e32 v112, v180
	v_mov_b32_e32 v113, v181
	v_mul_f32_e32 v117, v117, v117
	v_mul_f32_e32 v125, v125, v125
	v_fmac_f32_e32 v123, v122, v122
	v_fmac_f32_e32 v117, v116, v116
	v_mul_f32_e32 v119, v119, v119
	v_fmac_f32_e32 v125, v124, v124
	v_add_f32_e32 v116, v123, v117
	v_fmac_f32_e32 v119, v118, v118
	v_add_f32_e32 v116, v125, v116
	v_add_f32_e32 v122, v119, v116
	global_store_dwordx4 v[120:121], v[106:109], off
	v_lshlrev_b32_e32 v116, 16, v110
	v_and_b32_e32 v117, 0xffff0000, v110
	v_lshlrev_b32_e32 v110, 16, v111
	v_and_b32_e32 v111, 0xffff0000, v111
	v_lshlrev_b32_e32 v118, 16, v112
	v_and_b32_e32 v119, 0xffff0000, v112
	v_lshlrev_b32_e32 v112, 16, v113
	v_and_b32_e32 v113, 0xffff0000, v113
	v_pk_add_f32 v[104:105], v[104:105], v[110:111]
	v_pk_add_f32 v[102:103], v[102:103], v[116:117]
	v_pk_add_f32 v[110:111], v[100:101], v[112:113]
	v_pk_add_f32 v[112:113], v[98:99], v[118:119]
	v_mul_f32_e32 v98, v103, v103
	v_mul_f32_e32 v99, v105, v105
	v_mul_f32_e32 v100, v113, v113
	v_fmac_f32_e32 v98, v102, v102
	v_fmac_f32_e32 v99, v104, v104
	v_mul_f32_e32 v101, v111, v111
	v_fmac_f32_e32 v100, v112, v112
	v_add_f32_e32 v98, v98, v99
	v_add_f32_e32 v98, v100, v98
	v_fmac_f32_e32 v101, v110, v110
	v_add_f32_e32 v98, v101, v98
	v_add_f32_e32 v98, v122, v98
	ds_bpermute_b32 v99, v164, v98
	v_cvt_pk_bf16_f32 v100, v102, v103
	v_cvt_pk_bf16_f32 v101, v104, v105
	v_cvt_pk_bf16_f32 v102, v112, v113
	v_cvt_pk_bf16_f32 v103, v110, v111
	s_waitcnt lgkmcnt(0)
	v_add_f32_e32 v98, v98, v99
	ds_bpermute_b32 v99, v165, v98
	global_store_dwordx4 v[120:121], v[100:103], off offset:256
	s_and_saveexec_b64 s[48:49], s[38:39]
	s_cbranch_execz .LBB0_60
	v_lshlrev_b64 v[100:101], 6, v[114:115]
	v_lshl_add_u64 v[100:101], s[78:79], 0, v[100:101]
	v_lshl_add_u64 v[100:101], s[14:15], 2, v[100:101]
	s_lshl_b32 s24, s56, 2
	v_lshl_add_u64 v[100:101], v[100:101], 0, s[24:25]
	s_waitcnt lgkmcnt(0)
	v_add_f32_e32 v98, v98, v99
	global_store_dword v[100:101], v98, off
.LBB0_60:
	s_or_b64 exec, exec, s[48:49]
	v_or_b32_e32 v98, 32, v146
	s_waitcnt lgkmcnt(0)
	v_ashrrev_i32_e32 v99, 31, v98
	v_lshlrev_b64 v[100:101], 11, v[98:99]
	v_lshl_add_u64 v[100:101], s[18:19], 0, v[100:101]
	v_lshl_add_u64 v[104:105], v[144:145], 1, v[100:101]
	v_mov_b32_e32 v100, v182
	v_mov_b32_e32 v101, v183
	v_mov_b32_e32 v102, v184
	v_mov_b32_e32 v103, v185
	v_lshlrev_b32_e32 v106, 16, v100
	v_and_b32_e32 v107, 0xffff0000, v100
	v_lshlrev_b32_e32 v100, 16, v101
	v_and_b32_e32 v101, 0xffff0000, v101
	v_lshlrev_b32_e32 v108, 16, v102
	v_and_b32_e32 v109, 0xffff0000, v102
	v_lshlrev_b32_e32 v102, 16, v103
	v_and_b32_e32 v103, 0xffff0000, v103
	v_pk_add_f32 v[100:101], v[96:97], v[100:101]
	v_pk_add_f32 v[106:107], v[94:95], v[106:107]
	v_pk_add_f32 v[102:103], v[92:93], v[102:103]
	v_pk_add_f32 v[108:109], v[90:91], v[108:109]
	v_cvt_pk_bf16_f32 v90, v106, v107
	v_cvt_pk_bf16_f32 v91, v100, v101
	v_mul_f32_e32 v107, v107, v107
	v_cvt_pk_bf16_f32 v92, v108, v109
	v_cvt_pk_bf16_f32 v93, v102, v103
	v_mov_b32_e32 v94, v208
	v_mov_b32_e32 v95, v209
	v_mov_b32_e32 v96, v210
	v_mov_b32_e32 v97, v211
	v_mul_f32_e32 v101, v101, v101
	v_mul_f32_e32 v109, v109, v109
	v_fmac_f32_e32 v107, v106, v106
	v_fmac_f32_e32 v101, v100, v100
	v_mul_f32_e32 v103, v103, v103
	v_fmac_f32_e32 v109, v108, v108
	v_add_f32_e32 v100, v107, v101
	v_fmac_f32_e32 v103, v102, v102
	v_add_f32_e32 v100, v109, v100
	v_add_f32_e32 v106, v103, v100
	global_store_dwordx4 v[104:105], v[90:93], off
	v_lshlrev_b32_e32 v100, 16, v94
	v_and_b32_e32 v101, 0xffff0000, v94
	v_lshlrev_b32_e32 v94, 16, v95
	v_and_b32_e32 v95, 0xffff0000, v95
	v_lshlrev_b32_e32 v102, 16, v96
	v_and_b32_e32 v103, 0xffff0000, v96
	v_lshlrev_b32_e32 v96, 16, v97
	v_and_b32_e32 v97, 0xffff0000, v97
	v_pk_add_f32 v[88:89], v[88:89], v[94:95]
	v_pk_add_f32 v[86:87], v[86:87], v[100:101]
	v_pk_add_f32 v[94:95], v[84:85], v[96:97]
	v_pk_add_f32 v[96:97], v[82:83], v[102:103]
	v_mul_f32_e32 v82, v87, v87
	v_mul_f32_e32 v83, v89, v89
	v_mul_f32_e32 v84, v97, v97
	v_fmac_f32_e32 v82, v86, v86
	v_fmac_f32_e32 v83, v88, v88
	v_mul_f32_e32 v85, v95, v95
	v_fmac_f32_e32 v84, v96, v96
	v_add_f32_e32 v82, v82, v83
	v_add_f32_e32 v82, v84, v82
	v_fmac_f32_e32 v85, v94, v94
	v_add_f32_e32 v82, v85, v82
	v_add_f32_e32 v82, v106, v82
	ds_bpermute_b32 v83, v164, v82
	v_cvt_pk_bf16_f32 v84, v86, v87
	v_cvt_pk_bf16_f32 v85, v88, v89
	v_cvt_pk_bf16_f32 v86, v96, v97
	v_cvt_pk_bf16_f32 v87, v94, v95
	s_waitcnt lgkmcnt(0)
	v_add_f32_e32 v82, v82, v83
	ds_bpermute_b32 v83, v165, v82
	global_store_dwordx4 v[104:105], v[84:87], off offset:256
	s_and_saveexec_b64 s[48:49], s[38:39]
	s_cbranch_execz .LBB0_62
	v_lshlrev_b64 v[84:85], 6, v[98:99]
	v_lshl_add_u64 v[84:85], s[78:79], 0, v[84:85]
	v_lshl_add_u64 v[84:85], s[14:15], 2, v[84:85]
	s_lshl_b32 s24, s56, 2
	v_lshl_add_u64 v[84:85], v[84:85], 0, s[24:25]
	s_waitcnt lgkmcnt(0)
	v_add_f32_e32 v82, v82, v83
	global_store_dword v[84:85], v82, off
.LBB0_62:
	s_or_b64 exec, exec, s[48:49]
	v_or_b32_e32 v82, 48, v146
	s_waitcnt lgkmcnt(0)
	v_ashrrev_i32_e32 v83, 31, v82
	v_lshlrev_b64 v[84:85], 11, v[82:83]
	v_lshl_add_u64 v[84:85], s[18:19], 0, v[84:85]
	v_lshl_add_u64 v[88:89], v[144:145], 1, v[84:85]
	v_mov_b32_e32 v84, v212
	v_mov_b32_e32 v85, v213
	v_mov_b32_e32 v86, v214
	v_mov_b32_e32 v87, v215
	v_lshlrev_b32_e32 v90, 16, v84
	v_and_b32_e32 v91, 0xffff0000, v84
	v_lshlrev_b32_e32 v84, 16, v85
	v_and_b32_e32 v85, 0xffff0000, v85
	v_lshlrev_b32_e32 v92, 16, v86
	v_and_b32_e32 v93, 0xffff0000, v86
	v_lshlrev_b32_e32 v86, 16, v87
	v_and_b32_e32 v87, 0xffff0000, v87
	v_pk_add_f32 v[84:85], v[80:81], v[84:85]
	v_pk_add_f32 v[90:91], v[78:79], v[90:91]
	v_pk_add_f32 v[86:87], v[76:77], v[86:87]
	v_pk_add_f32 v[92:93], v[74:75], v[92:93]
	v_cvt_pk_bf16_f32 v74, v90, v91
	v_cvt_pk_bf16_f32 v75, v84, v85
	v_mul_f32_e32 v91, v91, v91
	v_cvt_pk_bf16_f32 v76, v92, v93
	v_cvt_pk_bf16_f32 v77, v86, v87
	v_mov_b32_e32 v78, v216
	v_mov_b32_e32 v79, v217
	v_mov_b32_e32 v80, v218
	v_mov_b32_e32 v81, v219
	v_mul_f32_e32 v85, v85, v85
	v_mul_f32_e32 v93, v93, v93
	v_fmac_f32_e32 v91, v90, v90
	v_fmac_f32_e32 v85, v84, v84
	v_mul_f32_e32 v87, v87, v87
	v_fmac_f32_e32 v93, v92, v92
	v_add_f32_e32 v84, v91, v85
	v_fmac_f32_e32 v87, v86, v86
	v_add_f32_e32 v84, v93, v84
	v_add_f32_e32 v90, v87, v84
	global_store_dwordx4 v[88:89], v[74:77], off
	v_lshlrev_b32_e32 v84, 16, v78
	v_and_b32_e32 v85, 0xffff0000, v78
	v_lshlrev_b32_e32 v78, 16, v79
	v_and_b32_e32 v79, 0xffff0000, v79
	v_lshlrev_b32_e32 v86, 16, v80
	v_and_b32_e32 v87, 0xffff0000, v80
	v_lshlrev_b32_e32 v80, 16, v81
	v_and_b32_e32 v81, 0xffff0000, v81
	v_pk_add_f32 v[72:73], v[72:73], v[78:79]
	v_pk_add_f32 v[70:71], v[70:71], v[84:85]
	v_pk_add_f32 v[78:79], v[68:69], v[80:81]
	v_pk_add_f32 v[80:81], v[66:67], v[86:87]
	v_mul_f32_e32 v66, v71, v71
	v_mul_f32_e32 v67, v73, v73
	v_mul_f32_e32 v68, v81, v81
	v_fmac_f32_e32 v66, v70, v70
	v_fmac_f32_e32 v67, v72, v72
	v_mul_f32_e32 v69, v79, v79
	v_fmac_f32_e32 v68, v80, v80
	v_add_f32_e32 v66, v66, v67
	v_add_f32_e32 v66, v68, v66
	v_fmac_f32_e32 v69, v78, v78
	v_add_f32_e32 v66, v69, v66
	v_add_f32_e32 v66, v90, v66
	ds_bpermute_b32 v67, v164, v66
	v_cvt_pk_bf16_f32 v68, v70, v71
	v_cvt_pk_bf16_f32 v69, v72, v73
	v_cvt_pk_bf16_f32 v70, v80, v81
	v_cvt_pk_bf16_f32 v71, v78, v79
	s_waitcnt lgkmcnt(0)
	v_add_f32_e32 v66, v66, v67
	ds_bpermute_b32 v67, v165, v66
	global_store_dwordx4 v[88:89], v[68:71], off offset:256
	s_and_saveexec_b64 s[48:49], s[38:39]
	s_cbranch_execz .LBB0_64
	v_lshlrev_b64 v[68:69], 6, v[82:83]
	v_lshl_add_u64 v[68:69], s[78:79], 0, v[68:69]
	v_lshl_add_u64 v[68:69], s[14:15], 2, v[68:69]
	s_lshl_b32 s24, s56, 2
	v_lshl_add_u64 v[68:69], v[68:69], 0, s[24:25]
	s_waitcnt lgkmcnt(0)
	v_add_f32_e32 v66, v66, v67
	global_store_dword v[68:69], v66, off
.LBB0_64:
	s_or_b64 exec, exec, s[48:49]
	v_add_u32_e32 v66, 0x80, v146
	s_waitcnt lgkmcnt(0)
	v_ashrrev_i32_e32 v67, 31, v66
	v_lshlrev_b64 v[68:69], 11, v[66:67]
	v_lshl_add_u64 v[68:69], s[18:19], 0, v[68:69]
	v_lshl_add_u64 v[72:73], v[144:145], 1, v[68:69]
	v_mov_b32_e32 v68, v220
	v_mov_b32_e32 v69, v221
	v_mov_b32_e32 v70, v222
	v_mov_b32_e32 v71, v223
	v_lshlrev_b32_e32 v74, 16, v68
	v_and_b32_e32 v75, 0xffff0000, v68
	v_lshlrev_b32_e32 v68, 16, v69
	v_and_b32_e32 v69, 0xffff0000, v69
	v_lshlrev_b32_e32 v76, 16, v70
	v_and_b32_e32 v77, 0xffff0000, v70
	v_lshlrev_b32_e32 v70, 16, v71
	v_and_b32_e32 v71, 0xffff0000, v71
	v_pk_add_f32 v[68:69], v[64:65], v[68:69]
	v_pk_add_f32 v[74:75], v[62:63], v[74:75]
	v_pk_add_f32 v[70:71], v[60:61], v[70:71]
	v_pk_add_f32 v[76:77], v[58:59], v[76:77]
	v_cvt_pk_bf16_f32 v58, v74, v75
	v_cvt_pk_bf16_f32 v59, v68, v69
	v_mul_f32_e32 v75, v75, v75
	v_cvt_pk_bf16_f32 v60, v76, v77
	v_cvt_pk_bf16_f32 v61, v70, v71
	v_mov_b32_e32 v62, v224
	v_mov_b32_e32 v63, v225
	v_mov_b32_e32 v64, v226
	v_mov_b32_e32 v65, v227
	v_mul_f32_e32 v69, v69, v69
	v_mul_f32_e32 v77, v77, v77
	v_fmac_f32_e32 v75, v74, v74
	v_fmac_f32_e32 v69, v68, v68
	v_mul_f32_e32 v71, v71, v71
	v_fmac_f32_e32 v77, v76, v76
	v_add_f32_e32 v68, v75, v69
	v_fmac_f32_e32 v71, v70, v70
	v_add_f32_e32 v68, v77, v68
	v_add_f32_e32 v74, v71, v68
	global_store_dwordx4 v[72:73], v[58:61], off
	v_lshlrev_b32_e32 v68, 16, v62
	v_and_b32_e32 v69, 0xffff0000, v62
	v_lshlrev_b32_e32 v62, 16, v63
	v_and_b32_e32 v63, 0xffff0000, v63
	v_lshlrev_b32_e32 v70, 16, v64
	v_and_b32_e32 v71, 0xffff0000, v64
	v_lshlrev_b32_e32 v64, 16, v65
	v_and_b32_e32 v65, 0xffff0000, v65
	v_pk_add_f32 v[56:57], v[56:57], v[62:63]
	v_pk_add_f32 v[54:55], v[54:55], v[68:69]
	v_pk_add_f32 v[62:63], v[52:53], v[64:65]
	v_pk_add_f32 v[64:65], v[50:51], v[70:71]
	v_mul_f32_e32 v50, v55, v55
	v_mul_f32_e32 v51, v57, v57
	v_mul_f32_e32 v52, v65, v65
	v_fmac_f32_e32 v50, v54, v54
	v_fmac_f32_e32 v51, v56, v56
	v_mul_f32_e32 v53, v63, v63
	v_fmac_f32_e32 v52, v64, v64
	v_add_f32_e32 v50, v50, v51
	v_add_f32_e32 v50, v52, v50
	v_fmac_f32_e32 v53, v62, v62
	v_add_f32_e32 v50, v53, v50
	v_add_f32_e32 v50, v74, v50
	ds_bpermute_b32 v51, v164, v50
	v_cvt_pk_bf16_f32 v52, v54, v55
	v_cvt_pk_bf16_f32 v53, v56, v57
	v_cvt_pk_bf16_f32 v54, v64, v65
	v_cvt_pk_bf16_f32 v55, v62, v63
	s_waitcnt lgkmcnt(0)
	v_add_f32_e32 v50, v50, v51
	ds_bpermute_b32 v51, v165, v50
	global_store_dwordx4 v[72:73], v[52:55], off offset:256
	s_and_saveexec_b64 s[48:49], s[38:39]
	s_cbranch_execz .LBB0_66
	v_lshlrev_b64 v[52:53], 6, v[66:67]
	v_lshl_add_u64 v[52:53], s[78:79], 0, v[52:53]
	v_lshl_add_u64 v[52:53], s[14:15], 2, v[52:53]
	s_lshl_b32 s24, s56, 2
	v_lshl_add_u64 v[52:53], v[52:53], 0, s[24:25]
	s_waitcnt lgkmcnt(0)
	v_add_f32_e32 v50, v50, v51
	global_store_dword v[52:53], v50, off
.LBB0_66:
	s_or_b64 exec, exec, s[48:49]
	v_add_u32_e32 v50, 0x90, v146
	s_waitcnt lgkmcnt(0)
	v_ashrrev_i32_e32 v51, 31, v50
	v_lshlrev_b64 v[52:53], 11, v[50:51]
	v_lshl_add_u64 v[52:53], s[18:19], 0, v[52:53]
	v_lshl_add_u64 v[56:57], v[144:145], 1, v[52:53]
	v_mov_b32_e32 v52, v228
	v_mov_b32_e32 v53, v229
	v_mov_b32_e32 v54, v230
	v_mov_b32_e32 v55, v231
	v_lshlrev_b32_e32 v58, 16, v52
	v_and_b32_e32 v59, 0xffff0000, v52
	v_lshlrev_b32_e32 v52, 16, v53
	v_and_b32_e32 v53, 0xffff0000, v53
	v_lshlrev_b32_e32 v60, 16, v54
	v_and_b32_e32 v61, 0xffff0000, v54
	v_lshlrev_b32_e32 v54, 16, v55
	v_and_b32_e32 v55, 0xffff0000, v55
	v_pk_add_f32 v[52:53], v[48:49], v[52:53]
	v_pk_add_f32 v[58:59], v[46:47], v[58:59]
	v_pk_add_f32 v[54:55], v[44:45], v[54:55]
	v_pk_add_f32 v[60:61], v[42:43], v[60:61]
	v_cvt_pk_bf16_f32 v42, v58, v59
	v_cvt_pk_bf16_f32 v43, v52, v53
	v_mul_f32_e32 v59, v59, v59
	v_cvt_pk_bf16_f32 v44, v60, v61
	v_cvt_pk_bf16_f32 v45, v54, v55
	v_mov_b32_e32 v46, v232
	v_mov_b32_e32 v47, v233
	v_mov_b32_e32 v48, v234
	v_mov_b32_e32 v49, v235
	v_mul_f32_e32 v53, v53, v53
	v_mul_f32_e32 v61, v61, v61
	v_fmac_f32_e32 v59, v58, v58
	v_fmac_f32_e32 v53, v52, v52
	v_mul_f32_e32 v55, v55, v55
	v_fmac_f32_e32 v61, v60, v60
	v_add_f32_e32 v52, v59, v53
	v_fmac_f32_e32 v55, v54, v54
	v_add_f32_e32 v52, v61, v52
	v_add_f32_e32 v58, v55, v52
	global_store_dwordx4 v[56:57], v[42:45], off
	v_lshlrev_b32_e32 v52, 16, v46
	v_and_b32_e32 v53, 0xffff0000, v46
	v_lshlrev_b32_e32 v46, 16, v47
	v_and_b32_e32 v47, 0xffff0000, v47
	v_lshlrev_b32_e32 v54, 16, v48
	v_and_b32_e32 v55, 0xffff0000, v48
	v_lshlrev_b32_e32 v48, 16, v49
	v_and_b32_e32 v49, 0xffff0000, v49
	v_pk_add_f32 v[40:41], v[40:41], v[46:47]
	v_pk_add_f32 v[38:39], v[38:39], v[52:53]
	v_pk_add_f32 v[46:47], v[36:37], v[48:49]
	v_pk_add_f32 v[48:49], v[34:35], v[54:55]
	v_mul_f32_e32 v34, v39, v39
	v_mul_f32_e32 v35, v41, v41
	v_mul_f32_e32 v36, v49, v49
	v_fmac_f32_e32 v34, v38, v38
	v_fmac_f32_e32 v35, v40, v40
	v_mul_f32_e32 v37, v47, v47
	v_fmac_f32_e32 v36, v48, v48
	v_add_f32_e32 v34, v34, v35
	v_add_f32_e32 v34, v36, v34
	v_fmac_f32_e32 v37, v46, v46
	v_add_f32_e32 v34, v37, v34
	v_add_f32_e32 v34, v58, v34
	ds_bpermute_b32 v35, v164, v34
	v_cvt_pk_bf16_f32 v36, v38, v39
	v_cvt_pk_bf16_f32 v37, v40, v41
	v_cvt_pk_bf16_f32 v38, v48, v49
	v_cvt_pk_bf16_f32 v39, v46, v47
	s_waitcnt lgkmcnt(0)
	v_add_f32_e32 v34, v34, v35
	ds_bpermute_b32 v35, v165, v34
	global_store_dwordx4 v[56:57], v[36:39], off offset:256
	s_and_saveexec_b64 s[48:49], s[38:39]
	s_cbranch_execz .LBB0_68
	v_lshlrev_b64 v[36:37], 6, v[50:51]
	v_lshl_add_u64 v[36:37], s[78:79], 0, v[36:37]
	v_lshl_add_u64 v[36:37], s[14:15], 2, v[36:37]
	s_lshl_b32 s24, s56, 2
	v_lshl_add_u64 v[36:37], v[36:37], 0, s[24:25]
	s_waitcnt lgkmcnt(0)
	v_add_f32_e32 v34, v34, v35
	global_store_dword v[36:37], v34, off
.LBB0_68:
	s_or_b64 exec, exec, s[48:49]
	v_add_u32_e32 v34, 0xa0, v146
	s_waitcnt lgkmcnt(0)
	v_ashrrev_i32_e32 v35, 31, v34
	v_lshlrev_b64 v[36:37], 11, v[34:35]
	v_lshl_add_u64 v[36:37], s[18:19], 0, v[36:37]
	v_lshl_add_u64 v[40:41], v[144:145], 1, v[36:37]
	v_mov_b32_e32 v36, v236
	v_mov_b32_e32 v37, v237
	v_mov_b32_e32 v38, v238
	v_mov_b32_e32 v39, v239
	v_lshlrev_b32_e32 v42, 16, v36
	v_and_b32_e32 v43, 0xffff0000, v36
	v_lshlrev_b32_e32 v36, 16, v37
	v_and_b32_e32 v37, 0xffff0000, v37
	v_lshlrev_b32_e32 v44, 16, v38
	v_and_b32_e32 v45, 0xffff0000, v38
	v_lshlrev_b32_e32 v38, 16, v39
	v_and_b32_e32 v39, 0xffff0000, v39
	v_pk_add_f32 v[36:37], v[32:33], v[36:37]
	v_pk_add_f32 v[42:43], v[30:31], v[42:43]
	v_pk_add_f32 v[38:39], v[28:29], v[38:39]
	v_pk_add_f32 v[44:45], v[26:27], v[44:45]
	v_cvt_pk_bf16_f32 v26, v42, v43
	v_cvt_pk_bf16_f32 v27, v36, v37
	v_mul_f32_e32 v43, v43, v43
	v_cvt_pk_bf16_f32 v28, v44, v45
	v_cvt_pk_bf16_f32 v29, v38, v39
	v_mov_b32_e32 v30, v240
	v_mov_b32_e32 v31, v241
	v_mov_b32_e32 v32, v242
	v_mov_b32_e32 v33, v243
	v_mul_f32_e32 v37, v37, v37
	v_mul_f32_e32 v45, v45, v45
	v_fmac_f32_e32 v43, v42, v42
	v_fmac_f32_e32 v37, v36, v36
	v_mul_f32_e32 v39, v39, v39
	v_fmac_f32_e32 v45, v44, v44
	v_add_f32_e32 v36, v43, v37
	v_fmac_f32_e32 v39, v38, v38
	v_add_f32_e32 v36, v45, v36
	v_add_f32_e32 v42, v39, v36
	global_store_dwordx4 v[40:41], v[26:29], off
	v_lshlrev_b32_e32 v36, 16, v30
	v_and_b32_e32 v37, 0xffff0000, v30
	v_lshlrev_b32_e32 v30, 16, v31
	v_and_b32_e32 v31, 0xffff0000, v31
	v_lshlrev_b32_e32 v38, 16, v32
	v_and_b32_e32 v39, 0xffff0000, v32
	v_pk_add_f32 v[24:25], v[24:25], v[30:31]
	v_pk_add_f32 v[22:23], v[22:23], v[36:37]
	v_lshlrev_b32_e32 v32, 16, v33
	v_and_b32_e32 v33, 0xffff0000, v33
	v_pk_add_f32 v[30:31], v[16:17], v[38:39]
	v_mul_f32_e32 v16, v23, v23
	v_mul_f32_e32 v17, v25, v25
	v_pk_add_f32 v[18:19], v[18:19], v[32:33]
	v_mul_f32_e32 v32, v31, v31
	v_fmac_f32_e32 v16, v22, v22
	v_fmac_f32_e32 v17, v24, v24
	v_mul_f32_e32 v33, v19, v19
	v_fmac_f32_e32 v32, v30, v30
	v_add_f32_e32 v16, v16, v17
	v_add_f32_e32 v16, v32, v16
	v_fmac_f32_e32 v33, v18, v18
	v_add_f32_e32 v16, v33, v16
	v_add_f32_e32 v16, v42, v16
	ds_bpermute_b32 v17, v164, v16
	v_cvt_pk_bf16_f32 v22, v22, v23
	v_cvt_pk_bf16_f32 v23, v24, v25
	v_cvt_pk_bf16_f32 v24, v30, v31
	v_cvt_pk_bf16_f32 v25, v18, v19
	s_waitcnt lgkmcnt(0)
	v_add_f32_e32 v16, v16, v17
	ds_bpermute_b32 v17, v165, v16
	global_store_dwordx4 v[40:41], v[22:25], off offset:256
	s_and_saveexec_b64 s[48:49], s[38:39]
	s_cbranch_execz .LBB0_70
	v_lshlrev_b64 v[18:19], 6, v[34:35]
	v_lshl_add_u64 v[18:19], s[78:79], 0, v[18:19]
	v_lshl_add_u64 v[18:19], s[14:15], 2, v[18:19]
	s_lshl_b32 s24, s56, 2
	v_lshl_add_u64 v[18:19], v[18:19], 0, s[24:25]
	s_waitcnt lgkmcnt(0)
	v_add_f32_e32 v16, v16, v17
	global_store_dword v[18:19], v16, off
.LBB0_70:
	s_or_b64 exec, exec, s[48:49]
	v_add_u32_e32 v16, 0xb0, v146
	s_waitcnt lgkmcnt(0)
	v_ashrrev_i32_e32 v17, 31, v16
	v_lshlrev_b64 v[18:19], 11, v[16:17]
	v_lshl_add_u64 v[18:19], s[18:19], 0, v[18:19]
	v_lshl_add_u64 v[18:19], v[144:145], 1, v[18:19]
	v_mov_b32_e32 v22, v244
	v_mov_b32_e32 v23, v245
	v_mov_b32_e32 v24, v246
	v_mov_b32_e32 v25, v247
	v_lshlrev_b32_e32 v26, 16, v22
	v_and_b32_e32 v27, 0xffff0000, v22
	v_lshlrev_b32_e32 v22, 16, v23
	v_and_b32_e32 v23, 0xffff0000, v23
	v_lshlrev_b32_e32 v28, 16, v24
	v_and_b32_e32 v29, 0xffff0000, v24
	v_lshlrev_b32_e32 v24, 16, v25
	v_and_b32_e32 v25, 0xffff0000, v25
	v_pk_add_f32 v[22:23], v[14:15], v[22:23]
	v_pk_add_f32 v[26:27], v[12:13], v[26:27]
	v_pk_add_f32 v[24:25], v[10:11], v[24:25]
	v_pk_add_f32 v[28:29], v[8:9], v[28:29]
	v_cvt_pk_bf16_f32 v8, v26, v27
	v_cvt_pk_bf16_f32 v9, v22, v23
	v_mul_f32_e32 v27, v27, v27
	v_cvt_pk_bf16_f32 v10, v28, v29
	v_cvt_pk_bf16_f32 v11, v24, v25
	v_mov_b32_e32 v12, v248
	v_mov_b32_e32 v13, v249
	v_mov_b32_e32 v14, v250
	v_mov_b32_e32 v15, v251
	v_mul_f32_e32 v23, v23, v23
	v_mul_f32_e32 v29, v29, v29
	v_fmac_f32_e32 v27, v26, v26
	v_fmac_f32_e32 v23, v22, v22
	v_mul_f32_e32 v25, v25, v25
	v_fmac_f32_e32 v29, v28, v28
	v_add_f32_e32 v22, v27, v23
	v_fmac_f32_e32 v25, v24, v24
	v_add_f32_e32 v22, v29, v22
	v_add_f32_e32 v26, v25, v22
	global_store_dwordx4 v[18:19], v[8:11], off
	v_lshlrev_b32_e32 v22, 16, v12
	v_and_b32_e32 v23, 0xffff0000, v12
	v_lshlrev_b32_e32 v12, 16, v13
	v_and_b32_e32 v13, 0xffff0000, v13
	v_lshlrev_b32_e32 v24, 16, v14
	v_and_b32_e32 v25, 0xffff0000, v14
	v_lshlrev_b32_e32 v14, 16, v15
	v_and_b32_e32 v15, 0xffff0000, v15
	v_pk_add_f32 v[6:7], v[6:7], v[12:13]
	v_pk_add_f32 v[4:5], v[4:5], v[22:23]
	v_pk_add_f32 v[12:13], v[2:3], v[14:15]
	v_pk_add_f32 v[14:15], v[0:1], v[24:25]
	v_mul_f32_e32 v0, v5, v5
	v_mul_f32_e32 v1, v7, v7
	v_mul_f32_e32 v2, v15, v15
	v_fmac_f32_e32 v0, v4, v4
	v_fmac_f32_e32 v1, v6, v6
	v_mul_f32_e32 v3, v13, v13
	v_fmac_f32_e32 v2, v14, v14
	v_add_f32_e32 v0, v0, v1
	v_add_f32_e32 v0, v2, v0
	v_fmac_f32_e32 v3, v12, v12
	v_add_f32_e32 v0, v3, v0
	v_add_f32_e32 v0, v26, v0
	ds_bpermute_b32 v1, v164, v0
	v_cvt_pk_bf16_f32 v2, v4, v5
	v_cvt_pk_bf16_f32 v3, v6, v7
	v_cvt_pk_bf16_f32 v4, v14, v15
	v_cvt_pk_bf16_f32 v5, v12, v13
	s_waitcnt lgkmcnt(0)
	v_add_f32_e32 v0, v0, v1
	ds_bpermute_b32 v1, v165, v0
	global_store_dwordx4 v[18:19], v[2:5], off offset:256
	s_and_saveexec_b64 s[48:49], s[38:39]
	s_cbranch_execz .LBB0_72
	v_lshlrev_b64 v[2:3], 6, v[16:17]
	v_lshl_add_u64 v[2:3], s[78:79], 0, v[2:3]
	v_lshl_add_u64 v[2:3], s[14:15], 2, v[2:3]
	s_lshl_b32 s24, s56, 2
	v_lshl_add_u64 v[2:3], v[2:3], 0, s[24:25]
	s_waitcnt lgkmcnt(0)
	v_add_f32_e32 v0, v0, v1
	global_store_dword v[2:3], v0, off

.LBB0_2069:
	v_lshl_add_u32 v146, s55, 8, v162
	v_lshl_or_b32 v144, s47, 5, v149
	v_ashrrev_i32_e32 v147, 31, v146
	v_lshl_or_b32 v144, s24, 8, v144
	v_lshlrev_b64 v[156:157], 11, v[146:147]
	v_lshl_add_u64 v[156:157], s[18:19], 0, v[156:157]
	v_ashrrev_i32_e32 v145, 31, v144
	v_lshl_add_u64 v[156:157], v[144:145], 1, v[156:157]
	global_load_dwordx4 v[168:171], v[156:157], off
	v_add_co_u32_e32 v188, vcc, 0x8000, v156
	s_nop 1
	v_addc_co_u32_e32 v189, vcc, 0, v157, vcc
	global_load_dwordx4 v[176:179], v[188:189], off
	global_load_dwordx4 v[180:183], v[188:189], off offset:256
	v_add_co_u32_e32 v188, vcc, 0x10000, v156
	s_nop 1
	v_addc_co_u32_e32 v189, vcc, 0, v157, vcc
	global_load_dwordx4 v[184:187], v[188:189], off
	global_load_dwordx4 v[208:211], v[188:189], off offset:256
	v_add_co_u32_e32 v188, vcc, 0x18000, v156
	s_nop 1
	v_addc_co_u32_e32 v189, vcc, 0, v157, vcc
	global_load_dwordx4 v[212:215], v[188:189], off
	global_load_dwordx4 v[216:219], v[188:189], off offset:256
	v_add_co_u32_e32 v188, vcc, 0x40000, v156
	s_nop 1
	v_addc_co_u32_e32 v189, vcc, 0, v157, vcc
	global_load_dwordx4 v[220:223], v[188:189], off
	global_load_dwordx4 v[224:227], v[188:189], off offset:256
	v_add_co_u32_e32 v188, vcc, 0x48000, v156
	s_nop 1
	v_addc_co_u32_e32 v189, vcc, 0, v157, vcc
	global_load_dwordx4 v[228:231], v[188:189], off
	global_load_dwordx4 v[232:235], v[188:189], off offset:256
	v_add_co_u32_e32 v188, vcc, 0x50000, v156
	s_nop 1
	v_addc_co_u32_e32 v189, vcc, 0, v157, vcc
	global_load_dwordx4 v[236:239], v[188:189], off
	global_load_dwordx4 v[240:243], v[188:189], off offset:256
	v_add_co_u32_e32 v188, vcc, 0x58000, v156
	s_nop 1
	v_addc_co_u32_e32 v189, vcc, 0, v157, vcc
	global_load_dwordx4 v[244:247], v[188:189], off
	global_load_dwordx4 v[248:251], v[188:189], off offset:256
	s_lshl_b32 s14, s24, 2
	s_ashr_i32 s15, s14, 31
	s_waitcnt vmcnt(14)
	v_lshlrev_b32_e32 v172, 16, v168
	v_and_b32_e32 v173, 0xffff0000, v168
	v_lshlrev_b32_e32 v168, 16, v169
	v_and_b32_e32 v169, 0xffff0000, v169
	v_lshlrev_b32_e32 v174, 16, v170
	v_and_b32_e32 v175, 0xffff0000, v170
	v_lshlrev_b32_e32 v170, 16, v171
	v_and_b32_e32 v171, 0xffff0000, v171
	v_pk_fma_f32 v[168:169], v[128:129], 0.5, v[168:169] op_sel_hi:[1,0,1]
	v_pk_fma_f32 v[172:173], v[126:127], 0.5, v[172:173] op_sel_hi:[1,0,1]
	v_pk_fma_f32 v[170:171], v[124:125], 0.5, v[170:171] op_sel_hi:[1,0,1]
	v_pk_fma_f32 v[174:175], v[122:123], 0.5, v[174:175] op_sel_hi:[1,0,1]
	v_cvt_pk_bf16_f32 v122, v172, v173
	v_cvt_pk_bf16_f32 v123, v168, v169
	v_mul_f32_e32 v154, v173, v173
	v_cvt_pk_bf16_f32 v124, v174, v175
	v_cvt_pk_bf16_f32 v125, v170, v171
	global_load_dwordx4 v[126:129], v[156:157], off offset:256
	v_mul_f32_e32 v155, v169, v169
	v_mul_f32_e32 v167, v175, v175
	v_fmac_f32_e32 v154, v172, v172
	v_fmac_f32_e32 v155, v168, v168
	v_mul_f32_e32 v169, v171, v171
	v_fmac_f32_e32 v167, v174, v174
	v_add_f32_e32 v154, v154, v155
	v_fmac_f32_e32 v169, v170, v170
	v_add_f32_e32 v154, v167, v154
	v_add_f32_e32 v154, v169, v154
	global_store_dwordx4 v[156:157], v[122:125], off
	s_waitcnt vmcnt(1)
	v_lshlrev_b32_e32 v168, 16, v126
	v_and_b32_e32 v169, 0xffff0000, v126
	v_lshlrev_b32_e32 v126, 16, v127
	v_and_b32_e32 v127, 0xffff0000, v127
	v_lshlrev_b32_e32 v170, 16, v128
	v_and_b32_e32 v171, 0xffff0000, v128
	v_lshlrev_b32_e32 v128, 16, v129
	v_and_b32_e32 v129, 0xffff0000, v129
	v_pk_fma_f32 v[120:121], v[120:121], 0.5, v[126:127] op_sel_hi:[1,0,1]
	v_pk_fma_f32 v[118:119], v[118:119], 0.5, v[168:169] op_sel_hi:[1,0,1]
	v_pk_fma_f32 v[126:127], v[116:117], 0.5, v[128:129] op_sel_hi:[1,0,1]
	v_pk_fma_f32 v[128:129], v[114:115], 0.5, v[170:171] op_sel_hi:[1,0,1]
	v_mul_f32_e32 v114, v119, v119
	v_mul_f32_e32 v115, v121, v121
	v_mul_f32_e32 v116, v129, v129
	v_fmac_f32_e32 v114, v118, v118
	v_fmac_f32_e32 v115, v120, v120
	v_mul_f32_e32 v117, v127, v127
	v_fmac_f32_e32 v116, v128, v128
	v_add_f32_e32 v114, v114, v115
	v_add_f32_e32 v114, v116, v114
	v_fmac_f32_e32 v117, v126, v126
	v_add_f32_e32 v114, v117, v114
	v_add_f32_e32 v114, v154, v114
	ds_bpermute_b32 v115, v164, v114
	v_cvt_pk_bf16_f32 v116, v118, v119
	v_cvt_pk_bf16_f32 v117, v120, v121
	v_cvt_pk_bf16_f32 v118, v128, v129
	v_cvt_pk_bf16_f32 v119, v126, v127
	s_waitcnt lgkmcnt(0)
	v_add_f32_e32 v114, v114, v115
	ds_bpermute_b32 v115, v165, v114
	global_store_dwordx4 v[156:157], v[116:119], off offset:256
	s_and_saveexec_b64 s[26:27], s[38:39]
	s_cbranch_execz .LBB0_2071
	v_lshlrev_b64 v[116:117], 6, v[146:147]
	v_lshl_add_u64 v[116:117], s[78:79], 0, v[116:117]
	v_lshl_add_u64 v[116:117], s[14:15], 2, v[116:117]
	s_lshl_b32 s24, s47, 2
	v_lshl_add_u64 v[116:117], v[116:117], 0, s[24:25]
	s_waitcnt lgkmcnt(0)
	v_add_f32_e32 v114, v114, v115
	global_store_dword v[116:117], v114, off
.LBB0_2071:
	s_or_b64 exec, exec, s[26:27]
	v_or_b32_e32 v114, 16, v146
	s_waitcnt lgkmcnt(0)
	v_ashrrev_i32_e32 v115, 31, v114
	v_lshlrev_b64 v[116:117], 11, v[114:115]
	v_lshl_add_u64 v[116:117], s[18:19], 0, v[116:117]
	v_lshl_add_u64 v[120:121], v[144:145], 1, v[116:117]
	v_mov_b32_e32 v116, v176
	v_mov_b32_e32 v117, v177
	v_mov_b32_e32 v118, v178
	v_mov_b32_e32 v119, v179
	v_lshlrev_b32_e32 v122, 16, v116
	v_and_b32_e32 v123, 0xffff0000, v116
	v_lshlrev_b32_e32 v116, 16, v117
	v_and_b32_e32 v117, 0xffff0000, v117
	v_lshlrev_b32_e32 v124, 16, v118
	v_and_b32_e32 v125, 0xffff0000, v118
	v_lshlrev_b32_e32 v118, 16, v119
	v_and_b32_e32 v119, 0xffff0000, v119
	v_pk_fma_f32 v[116:117], v[112:113], 0.5, v[116:117] op_sel_hi:[1,0,1]
	v_pk_fma_f32 v[122:123], v[110:111], 0.5, v[122:123] op_sel_hi:[1,0,1]
	v_pk_fma_f32 v[118:119], v[108:109], 0.5, v[118:119] op_sel_hi:[1,0,1]
	v_pk_fma_f32 v[124:125], v[106:107], 0.5, v[124:125] op_sel_hi:[1,0,1]
	v_cvt_pk_bf16_f32 v106, v122, v123
	v_cvt_pk_bf16_f32 v107, v116, v117
	v_mul_f32_e32 v123, v123, v123
	v_cvt_pk_bf16_f32 v108, v124, v125
	v_cvt_pk_bf16_f32 v109, v118, v119
	v_mov_b32_e32 v110, v180
	v_mov_b32_e32 v111, v181
	v_mov_b32_e32 v112, v182
	v_mov_b32_e32 v113, v183
	v_mul_f32_e32 v117, v117, v117
	v_mul_f32_e32 v125, v125, v125
	v_fmac_f32_e32 v123, v122, v122
	v_fmac_f32_e32 v117, v116, v116
	v_mul_f32_e32 v119, v119, v119
	v_fmac_f32_e32 v125, v124, v124
	v_add_f32_e32 v116, v123, v117
	v_fmac_f32_e32 v119, v118, v118
	v_add_f32_e32 v116, v125, v116
	v_add_f32_e32 v122, v119, v116
	global_store_dwordx4 v[120:121], v[106:109], off
	v_lshlrev_b32_e32 v116, 16, v110
	v_and_b32_e32 v117, 0xffff0000, v110
	v_lshlrev_b32_e32 v110, 16, v111
	v_and_b32_e32 v111, 0xffff0000, v111
	v_lshlrev_b32_e32 v118, 16, v112
	v_and_b32_e32 v119, 0xffff0000, v112
	v_lshlrev_b32_e32 v112, 16, v113
	v_and_b32_e32 v113, 0xffff0000, v113
	v_pk_fma_f32 v[104:105], v[104:105], 0.5, v[110:111] op_sel_hi:[1,0,1]
	v_pk_fma_f32 v[102:103], v[102:103], 0.5, v[116:117] op_sel_hi:[1,0,1]
	v_pk_fma_f32 v[110:111], v[100:101], 0.5, v[112:113] op_sel_hi:[1,0,1]
	v_pk_fma_f32 v[112:113], v[98:99], 0.5, v[118:119] op_sel_hi:[1,0,1]
	v_mul_f32_e32 v98, v103, v103
	v_mul_f32_e32 v99, v105, v105
	v_mul_f32_e32 v100, v113, v113
	v_fmac_f32_e32 v98, v102, v102
	v_fmac_f32_e32 v99, v104, v104
	v_mul_f32_e32 v101, v111, v111
	v_fmac_f32_e32 v100, v112, v112
	v_add_f32_e32 v98, v98, v99
	v_add_f32_e32 v98, v100, v98
	v_fmac_f32_e32 v101, v110, v110
	v_add_f32_e32 v98, v101, v98
	v_add_f32_e32 v98, v122, v98
	ds_bpermute_b32 v99, v164, v98
	v_cvt_pk_bf16_f32 v100, v102, v103
	v_cvt_pk_bf16_f32 v101, v104, v105
	v_cvt_pk_bf16_f32 v102, v112, v113
	v_cvt_pk_bf16_f32 v103, v110, v111
	s_waitcnt lgkmcnt(0)
	v_add_f32_e32 v98, v98, v99
	ds_bpermute_b32 v99, v165, v98
	global_store_dwordx4 v[120:121], v[100:103], off offset:256
	s_and_saveexec_b64 s[26:27], s[38:39]
	s_cbranch_execz .LBB0_2073
	v_lshlrev_b64 v[100:101], 6, v[114:115]
	v_lshl_add_u64 v[100:101], s[78:79], 0, v[100:101]
	v_lshl_add_u64 v[100:101], s[14:15], 2, v[100:101]
	s_lshl_b32 s24, s47, 2
	v_lshl_add_u64 v[100:101], v[100:101], 0, s[24:25]
	s_waitcnt lgkmcnt(0)
	v_add_f32_e32 v98, v98, v99
	global_store_dword v[100:101], v98, off
.LBB0_2073:
	s_or_b64 exec, exec, s[26:27]
	v_or_b32_e32 v98, 32, v146
	s_waitcnt lgkmcnt(0)
	v_ashrrev_i32_e32 v99, 31, v98
	v_lshlrev_b64 v[100:101], 11, v[98:99]
	v_lshl_add_u64 v[100:101], s[18:19], 0, v[100:101]
	v_lshl_add_u64 v[104:105], v[144:145], 1, v[100:101]
	v_mov_b32_e32 v100, v184
	v_mov_b32_e32 v101, v185
	v_mov_b32_e32 v102, v186
	v_mov_b32_e32 v103, v187
	v_lshlrev_b32_e32 v106, 16, v100
	v_and_b32_e32 v107, 0xffff0000, v100
	v_lshlrev_b32_e32 v100, 16, v101
	v_and_b32_e32 v101, 0xffff0000, v101
	v_lshlrev_b32_e32 v108, 16, v102
	v_and_b32_e32 v109, 0xffff0000, v102
	v_lshlrev_b32_e32 v102, 16, v103
	v_and_b32_e32 v103, 0xffff0000, v103
	v_pk_fma_f32 v[100:101], v[96:97], 0.5, v[100:101] op_sel_hi:[1,0,1]
	v_pk_fma_f32 v[106:107], v[94:95], 0.5, v[106:107] op_sel_hi:[1,0,1]
	v_pk_fma_f32 v[102:103], v[92:93], 0.5, v[102:103] op_sel_hi:[1,0,1]
	v_pk_fma_f32 v[108:109], v[90:91], 0.5, v[108:109] op_sel_hi:[1,0,1]
	v_cvt_pk_bf16_f32 v90, v106, v107
	v_cvt_pk_bf16_f32 v91, v100, v101
	v_mul_f32_e32 v107, v107, v107
	v_cvt_pk_bf16_f32 v92, v108, v109
	v_cvt_pk_bf16_f32 v93, v102, v103
	v_mov_b32_e32 v94, v208
	v_mov_b32_e32 v95, v209
	v_mov_b32_e32 v96, v210
	v_mov_b32_e32 v97, v211
	v_mul_f32_e32 v101, v101, v101
	v_mul_f32_e32 v109, v109, v109
	v_fmac_f32_e32 v107, v106, v106
	v_fmac_f32_e32 v101, v100, v100
	v_mul_f32_e32 v103, v103, v103
	v_fmac_f32_e32 v109, v108, v108
	v_add_f32_e32 v100, v107, v101
	v_fmac_f32_e32 v103, v102, v102
	v_add_f32_e32 v100, v109, v100
	v_add_f32_e32 v106, v103, v100
	global_store_dwordx4 v[104:105], v[90:93], off
	v_lshlrev_b32_e32 v100, 16, v94
	v_and_b32_e32 v101, 0xffff0000, v94
	v_lshlrev_b32_e32 v94, 16, v95
	v_and_b32_e32 v95, 0xffff0000, v95
	v_lshlrev_b32_e32 v102, 16, v96
	v_and_b32_e32 v103, 0xffff0000, v96
	v_lshlrev_b32_e32 v96, 16, v97
	v_and_b32_e32 v97, 0xffff0000, v97
	v_pk_fma_f32 v[88:89], v[88:89], 0.5, v[94:95] op_sel_hi:[1,0,1]
	v_pk_fma_f32 v[86:87], v[86:87], 0.5, v[100:101] op_sel_hi:[1,0,1]
	v_pk_fma_f32 v[94:95], v[84:85], 0.5, v[96:97] op_sel_hi:[1,0,1]
	v_pk_fma_f32 v[96:97], v[82:83], 0.5, v[102:103] op_sel_hi:[1,0,1]
	v_mul_f32_e32 v82, v87, v87
	v_mul_f32_e32 v83, v89, v89
	v_mul_f32_e32 v84, v97, v97
	v_fmac_f32_e32 v82, v86, v86
	v_fmac_f32_e32 v83, v88, v88
	v_mul_f32_e32 v85, v95, v95
	v_fmac_f32_e32 v84, v96, v96
	v_add_f32_e32 v82, v82, v83
	v_add_f32_e32 v82, v84, v82
	v_fmac_f32_e32 v85, v94, v94
	v_add_f32_e32 v82, v85, v82
	v_add_f32_e32 v82, v106, v82
	ds_bpermute_b32 v83, v164, v82
	v_cvt_pk_bf16_f32 v84, v86, v87
	v_cvt_pk_bf16_f32 v85, v88, v89
	v_cvt_pk_bf16_f32 v86, v96, v97
	v_cvt_pk_bf16_f32 v87, v94, v95
	s_waitcnt lgkmcnt(0)
	v_add_f32_e32 v82, v82, v83
	ds_bpermute_b32 v83, v165, v82
	global_store_dwordx4 v[104:105], v[84:87], off offset:256
	s_and_saveexec_b64 s[26:27], s[38:39]
	s_cbranch_execz .LBB0_2075
	v_lshlrev_b64 v[84:85], 6, v[98:99]
	v_lshl_add_u64 v[84:85], s[78:79], 0, v[84:85]
	v_lshl_add_u64 v[84:85], s[14:15], 2, v[84:85]
	s_lshl_b32 s24, s47, 2
	v_lshl_add_u64 v[84:85], v[84:85], 0, s[24:25]
	s_waitcnt lgkmcnt(0)
	v_add_f32_e32 v82, v82, v83
	global_store_dword v[84:85], v82, off
.LBB0_2075:
	s_or_b64 exec, exec, s[26:27]
	v_or_b32_e32 v82, 48, v146
	s_waitcnt lgkmcnt(0)
	v_ashrrev_i32_e32 v83, 31, v82
	v_lshlrev_b64 v[84:85], 11, v[82:83]
	v_lshl_add_u64 v[84:85], s[18:19], 0, v[84:85]
	v_lshl_add_u64 v[88:89], v[144:145], 1, v[84:85]
	v_mov_b32_e32 v84, v212
	v_mov_b32_e32 v85, v213
	v_mov_b32_e32 v86, v214
	v_mov_b32_e32 v87, v215
	v_lshlrev_b32_e32 v90, 16, v84
	v_and_b32_e32 v91, 0xffff0000, v84
	v_lshlrev_b32_e32 v84, 16, v85
	v_and_b32_e32 v85, 0xffff0000, v85
	v_lshlrev_b32_e32 v92, 16, v86
	v_and_b32_e32 v93, 0xffff0000, v86
	v_lshlrev_b32_e32 v86, 16, v87
	v_and_b32_e32 v87, 0xffff0000, v87
	v_pk_fma_f32 v[84:85], v[80:81], 0.5, v[84:85] op_sel_hi:[1,0,1]
	v_pk_fma_f32 v[90:91], v[78:79], 0.5, v[90:91] op_sel_hi:[1,0,1]
	v_pk_fma_f32 v[86:87], v[76:77], 0.5, v[86:87] op_sel_hi:[1,0,1]
	v_pk_fma_f32 v[92:93], v[74:75], 0.5, v[92:93] op_sel_hi:[1,0,1]
	v_cvt_pk_bf16_f32 v74, v90, v91
	v_cvt_pk_bf16_f32 v75, v84, v85
	v_mul_f32_e32 v91, v91, v91
	v_cvt_pk_bf16_f32 v76, v92, v93
	v_cvt_pk_bf16_f32 v77, v86, v87
	v_mov_b32_e32 v78, v216
	v_mov_b32_e32 v79, v217
	v_mov_b32_e32 v80, v218
	v_mov_b32_e32 v81, v219
	v_mul_f32_e32 v85, v85, v85
	v_mul_f32_e32 v93, v93, v93
	v_fmac_f32_e32 v91, v90, v90
	v_fmac_f32_e32 v85, v84, v84
	v_mul_f32_e32 v87, v87, v87
	v_fmac_f32_e32 v93, v92, v92
	v_add_f32_e32 v84, v91, v85
	v_fmac_f32_e32 v87, v86, v86
	v_add_f32_e32 v84, v93, v84
	v_add_f32_e32 v90, v87, v84
	global_store_dwordx4 v[88:89], v[74:77], off
	v_lshlrev_b32_e32 v84, 16, v78
	v_and_b32_e32 v85, 0xffff0000, v78
	v_lshlrev_b32_e32 v78, 16, v79
	v_and_b32_e32 v79, 0xffff0000, v79
	v_lshlrev_b32_e32 v86, 16, v80
	v_and_b32_e32 v87, 0xffff0000, v80
	v_lshlrev_b32_e32 v80, 16, v81
	v_and_b32_e32 v81, 0xffff0000, v81
	v_pk_fma_f32 v[72:73], v[72:73], 0.5, v[78:79] op_sel_hi:[1,0,1]
	v_pk_fma_f32 v[70:71], v[70:71], 0.5, v[84:85] op_sel_hi:[1,0,1]
	v_pk_fma_f32 v[78:79], v[68:69], 0.5, v[80:81] op_sel_hi:[1,0,1]
	v_pk_fma_f32 v[80:81], v[66:67], 0.5, v[86:87] op_sel_hi:[1,0,1]
	v_mul_f32_e32 v66, v71, v71
	v_mul_f32_e32 v67, v73, v73
	v_mul_f32_e32 v68, v81, v81
	v_fmac_f32_e32 v66, v70, v70
	v_fmac_f32_e32 v67, v72, v72
	v_mul_f32_e32 v69, v79, v79
	v_fmac_f32_e32 v68, v80, v80
	v_add_f32_e32 v66, v66, v67
	v_add_f32_e32 v66, v68, v66
	v_fmac_f32_e32 v69, v78, v78
	v_add_f32_e32 v66, v69, v66
	v_add_f32_e32 v66, v90, v66
	ds_bpermute_b32 v67, v164, v66
	v_cvt_pk_bf16_f32 v68, v70, v71
	v_cvt_pk_bf16_f32 v69, v72, v73
	v_cvt_pk_bf16_f32 v70, v80, v81
	v_cvt_pk_bf16_f32 v71, v78, v79
	s_waitcnt lgkmcnt(0)
	v_add_f32_e32 v66, v66, v67
	ds_bpermute_b32 v67, v165, v66
	global_store_dwordx4 v[88:89], v[68:71], off offset:256
	s_and_saveexec_b64 s[26:27], s[38:39]
	s_cbranch_execz .LBB0_2077
	v_lshlrev_b64 v[68:69], 6, v[82:83]
	v_lshl_add_u64 v[68:69], s[78:79], 0, v[68:69]
	v_lshl_add_u64 v[68:69], s[14:15], 2, v[68:69]
	s_lshl_b32 s24, s47, 2
	v_lshl_add_u64 v[68:69], v[68:69], 0, s[24:25]
	s_waitcnt lgkmcnt(0)
	v_add_f32_e32 v66, v66, v67
	global_store_dword v[68:69], v66, off
.LBB0_2077:
	s_or_b64 exec, exec, s[26:27]
	v_add_u32_e32 v66, 0x80, v146
	s_waitcnt lgkmcnt(0)
	v_ashrrev_i32_e32 v67, 31, v66
	v_lshlrev_b64 v[68:69], 11, v[66:67]
	v_lshl_add_u64 v[68:69], s[18:19], 0, v[68:69]
	v_lshl_add_u64 v[72:73], v[144:145], 1, v[68:69]
	v_mov_b32_e32 v68, v220
	v_mov_b32_e32 v69, v221
	v_mov_b32_e32 v70, v222
	v_mov_b32_e32 v71, v223
	v_lshlrev_b32_e32 v74, 16, v68
	v_and_b32_e32 v75, 0xffff0000, v68
	v_lshlrev_b32_e32 v68, 16, v69
	v_and_b32_e32 v69, 0xffff0000, v69
	v_lshlrev_b32_e32 v76, 16, v70
	v_and_b32_e32 v77, 0xffff0000, v70
	v_lshlrev_b32_e32 v70, 16, v71
	v_and_b32_e32 v71, 0xffff0000, v71
	v_pk_fma_f32 v[68:69], v[64:65], 0.5, v[68:69] op_sel_hi:[1,0,1]
	v_pk_fma_f32 v[74:75], v[62:63], 0.5, v[74:75] op_sel_hi:[1,0,1]
	v_pk_fma_f32 v[70:71], v[60:61], 0.5, v[70:71] op_sel_hi:[1,0,1]
	v_pk_fma_f32 v[76:77], v[58:59], 0.5, v[76:77] op_sel_hi:[1,0,1]
	v_cvt_pk_bf16_f32 v58, v74, v75
	v_cvt_pk_bf16_f32 v59, v68, v69
	v_mul_f32_e32 v75, v75, v75
	v_cvt_pk_bf16_f32 v60, v76, v77
	v_cvt_pk_bf16_f32 v61, v70, v71
	v_mov_b32_e32 v62, v224
	v_mov_b32_e32 v63, v225
	v_mov_b32_e32 v64, v226
	v_mov_b32_e32 v65, v227
	v_mul_f32_e32 v69, v69, v69
	v_mul_f32_e32 v77, v77, v77
	v_fmac_f32_e32 v75, v74, v74
	v_fmac_f32_e32 v69, v68, v68
	v_mul_f32_e32 v71, v71, v71
	v_fmac_f32_e32 v77, v76, v76
	v_add_f32_e32 v68, v75, v69
	v_fmac_f32_e32 v71, v70, v70
	v_add_f32_e32 v68, v77, v68
	v_add_f32_e32 v74, v71, v68
	global_store_dwordx4 v[72:73], v[58:61], off
	v_lshlrev_b32_e32 v68, 16, v62
	v_and_b32_e32 v69, 0xffff0000, v62
	v_lshlrev_b32_e32 v62, 16, v63
	v_and_b32_e32 v63, 0xffff0000, v63
	v_lshlrev_b32_e32 v70, 16, v64
	v_and_b32_e32 v71, 0xffff0000, v64
	v_lshlrev_b32_e32 v64, 16, v65
	v_and_b32_e32 v65, 0xffff0000, v65
	v_pk_fma_f32 v[56:57], v[56:57], 0.5, v[62:63] op_sel_hi:[1,0,1]
	v_pk_fma_f32 v[54:55], v[54:55], 0.5, v[68:69] op_sel_hi:[1,0,1]
	v_pk_fma_f32 v[62:63], v[52:53], 0.5, v[64:65] op_sel_hi:[1,0,1]
	v_pk_fma_f32 v[64:65], v[50:51], 0.5, v[70:71] op_sel_hi:[1,0,1]
	v_mul_f32_e32 v50, v55, v55
	v_mul_f32_e32 v51, v57, v57
	v_mul_f32_e32 v52, v65, v65
	v_fmac_f32_e32 v50, v54, v54
	v_fmac_f32_e32 v51, v56, v56
	v_mul_f32_e32 v53, v63, v63
	v_fmac_f32_e32 v52, v64, v64
	v_add_f32_e32 v50, v50, v51
	v_add_f32_e32 v50, v52, v50
	v_fmac_f32_e32 v53, v62, v62
	v_add_f32_e32 v50, v53, v50
	v_add_f32_e32 v50, v74, v50
	ds_bpermute_b32 v51, v164, v50
	v_cvt_pk_bf16_f32 v52, v54, v55
	v_cvt_pk_bf16_f32 v53, v56, v57
	v_cvt_pk_bf16_f32 v54, v64, v65
	v_cvt_pk_bf16_f32 v55, v62, v63
	s_waitcnt lgkmcnt(0)
	v_add_f32_e32 v50, v50, v51
	ds_bpermute_b32 v51, v165, v50
	global_store_dwordx4 v[72:73], v[52:55], off offset:256
	s_and_saveexec_b64 s[26:27], s[38:39]
	s_cbranch_execz .LBB0_2079
	v_lshlrev_b64 v[52:53], 6, v[66:67]
	v_lshl_add_u64 v[52:53], s[78:79], 0, v[52:53]
	v_lshl_add_u64 v[52:53], s[14:15], 2, v[52:53]
	s_lshl_b32 s24, s47, 2
	v_lshl_add_u64 v[52:53], v[52:53], 0, s[24:25]
	s_waitcnt lgkmcnt(0)
	v_add_f32_e32 v50, v50, v51
	global_store_dword v[52:53], v50, off
.LBB0_2079:
	s_or_b64 exec, exec, s[26:27]
	v_add_u32_e32 v50, 0x90, v146
	s_waitcnt lgkmcnt(0)
	v_ashrrev_i32_e32 v51, 31, v50
	v_lshlrev_b64 v[52:53], 11, v[50:51]
	v_lshl_add_u64 v[52:53], s[18:19], 0, v[52:53]
	v_lshl_add_u64 v[56:57], v[144:145], 1, v[52:53]
	v_mov_b32_e32 v52, v228
	v_mov_b32_e32 v53, v229
	v_mov_b32_e32 v54, v230
	v_mov_b32_e32 v55, v231
	v_lshlrev_b32_e32 v58, 16, v52
	v_and_b32_e32 v59, 0xffff0000, v52
	v_lshlrev_b32_e32 v52, 16, v53
	v_and_b32_e32 v53, 0xffff0000, v53
	v_lshlrev_b32_e32 v60, 16, v54
	v_and_b32_e32 v61, 0xffff0000, v54
	v_lshlrev_b32_e32 v54, 16, v55
	v_and_b32_e32 v55, 0xffff0000, v55
	v_pk_fma_f32 v[52:53], v[48:49], 0.5, v[52:53] op_sel_hi:[1,0,1]
	v_pk_fma_f32 v[58:59], v[46:47], 0.5, v[58:59] op_sel_hi:[1,0,1]
	v_pk_fma_f32 v[54:55], v[44:45], 0.5, v[54:55] op_sel_hi:[1,0,1]
	v_pk_fma_f32 v[60:61], v[42:43], 0.5, v[60:61] op_sel_hi:[1,0,1]
	v_cvt_pk_bf16_f32 v42, v58, v59
	v_cvt_pk_bf16_f32 v43, v52, v53
	v_mul_f32_e32 v59, v59, v59
	v_cvt_pk_bf16_f32 v44, v60, v61
	v_cvt_pk_bf16_f32 v45, v54, v55
	v_mov_b32_e32 v46, v232
	v_mov_b32_e32 v47, v233
	v_mov_b32_e32 v48, v234
	v_mov_b32_e32 v49, v235
	v_mul_f32_e32 v53, v53, v53
	v_mul_f32_e32 v61, v61, v61
	v_fmac_f32_e32 v59, v58, v58
	v_fmac_f32_e32 v53, v52, v52
	v_mul_f32_e32 v55, v55, v55
	v_fmac_f32_e32 v61, v60, v60
	v_add_f32_e32 v52, v59, v53
	v_fmac_f32_e32 v55, v54, v54
	v_add_f32_e32 v52, v61, v52
	v_add_f32_e32 v58, v55, v52
	global_store_dwordx4 v[56:57], v[42:45], off
	v_lshlrev_b32_e32 v52, 16, v46
	v_and_b32_e32 v53, 0xffff0000, v46
	v_lshlrev_b32_e32 v46, 16, v47
	v_and_b32_e32 v47, 0xffff0000, v47
	v_lshlrev_b32_e32 v54, 16, v48
	v_and_b32_e32 v55, 0xffff0000, v48
	v_lshlrev_b32_e32 v48, 16, v49
	v_and_b32_e32 v49, 0xffff0000, v49
	v_pk_fma_f32 v[40:41], v[40:41], 0.5, v[46:47] op_sel_hi:[1,0,1]
	v_pk_fma_f32 v[38:39], v[38:39], 0.5, v[52:53] op_sel_hi:[1,0,1]
	v_pk_fma_f32 v[46:47], v[36:37], 0.5, v[48:49] op_sel_hi:[1,0,1]
	v_pk_fma_f32 v[48:49], v[34:35], 0.5, v[54:55] op_sel_hi:[1,0,1]
	v_mul_f32_e32 v34, v39, v39
	v_mul_f32_e32 v35, v41, v41
	v_mul_f32_e32 v36, v49, v49
	v_fmac_f32_e32 v34, v38, v38
	v_fmac_f32_e32 v35, v40, v40
	v_mul_f32_e32 v37, v47, v47
	v_fmac_f32_e32 v36, v48, v48
	v_add_f32_e32 v34, v34, v35
	v_add_f32_e32 v34, v36, v34
	v_fmac_f32_e32 v37, v46, v46
	v_add_f32_e32 v34, v37, v34
	v_add_f32_e32 v34, v58, v34
	ds_bpermute_b32 v35, v164, v34
	v_cvt_pk_bf16_f32 v36, v38, v39
	v_cvt_pk_bf16_f32 v37, v40, v41
	v_cvt_pk_bf16_f32 v38, v48, v49
	v_cvt_pk_bf16_f32 v39, v46, v47
	s_waitcnt lgkmcnt(0)
	v_add_f32_e32 v34, v34, v35
	ds_bpermute_b32 v35, v165, v34
	global_store_dwordx4 v[56:57], v[36:39], off offset:256
	s_and_saveexec_b64 s[26:27], s[38:39]
	s_cbranch_execz .LBB0_2081
	v_lshlrev_b64 v[36:37], 6, v[50:51]
	v_lshl_add_u64 v[36:37], s[78:79], 0, v[36:37]
	v_lshl_add_u64 v[36:37], s[14:15], 2, v[36:37]
	s_lshl_b32 s24, s47, 2
	v_lshl_add_u64 v[36:37], v[36:37], 0, s[24:25]
	s_waitcnt lgkmcnt(0)
	v_add_f32_e32 v34, v34, v35
	global_store_dword v[36:37], v34, off
.LBB0_2081:
	s_or_b64 exec, exec, s[26:27]
	v_add_u32_e32 v34, 0xa0, v146
	s_waitcnt lgkmcnt(0)
	v_ashrrev_i32_e32 v35, 31, v34
	v_lshlrev_b64 v[36:37], 11, v[34:35]
	v_lshl_add_u64 v[36:37], s[18:19], 0, v[36:37]
	v_lshl_add_u64 v[40:41], v[144:145], 1, v[36:37]
	v_mov_b32_e32 v36, v236
	v_mov_b32_e32 v37, v237
	v_mov_b32_e32 v38, v238
	v_mov_b32_e32 v39, v239
	v_lshlrev_b32_e32 v42, 16, v36
	v_and_b32_e32 v43, 0xffff0000, v36
	v_lshlrev_b32_e32 v36, 16, v37
	v_and_b32_e32 v37, 0xffff0000, v37
	v_lshlrev_b32_e32 v44, 16, v38
	v_and_b32_e32 v45, 0xffff0000, v38
	v_lshlrev_b32_e32 v38, 16, v39
	v_and_b32_e32 v39, 0xffff0000, v39
	v_pk_fma_f32 v[36:37], v[32:33], 0.5, v[36:37] op_sel_hi:[1,0,1]
	v_pk_fma_f32 v[42:43], v[30:31], 0.5, v[42:43] op_sel_hi:[1,0,1]
	v_pk_fma_f32 v[38:39], v[28:29], 0.5, v[38:39] op_sel_hi:[1,0,1]
	v_pk_fma_f32 v[44:45], v[26:27], 0.5, v[44:45] op_sel_hi:[1,0,1]
	v_cvt_pk_bf16_f32 v26, v42, v43
	v_cvt_pk_bf16_f32 v27, v36, v37
	v_mul_f32_e32 v43, v43, v43
	v_cvt_pk_bf16_f32 v28, v44, v45
	v_cvt_pk_bf16_f32 v29, v38, v39
	v_mov_b32_e32 v30, v240
	v_mov_b32_e32 v31, v241
	v_mov_b32_e32 v32, v242
	v_mov_b32_e32 v33, v243
	v_mul_f32_e32 v37, v37, v37
	v_mul_f32_e32 v45, v45, v45
	v_fmac_f32_e32 v43, v42, v42
	v_fmac_f32_e32 v37, v36, v36
	v_mul_f32_e32 v39, v39, v39
	v_fmac_f32_e32 v45, v44, v44
	v_add_f32_e32 v36, v43, v37
	v_fmac_f32_e32 v39, v38, v38
	v_add_f32_e32 v36, v45, v36
	v_add_f32_e32 v42, v39, v36
	global_store_dwordx4 v[40:41], v[26:29], off
	v_lshlrev_b32_e32 v36, 16, v30
	v_and_b32_e32 v37, 0xffff0000, v30
	v_lshlrev_b32_e32 v30, 16, v31
	v_and_b32_e32 v31, 0xffff0000, v31
	v_lshlrev_b32_e32 v38, 16, v32
	v_and_b32_e32 v39, 0xffff0000, v32
	v_pk_fma_f32 v[24:25], v[24:25], 0.5, v[30:31] op_sel_hi:[1,0,1]
	v_pk_fma_f32 v[22:23], v[22:23], 0.5, v[36:37] op_sel_hi:[1,0,1]
	v_lshlrev_b32_e32 v32, 16, v33
	v_and_b32_e32 v33, 0xffff0000, v33
	v_pk_fma_f32 v[30:31], v[16:17], 0.5, v[38:39] op_sel_hi:[1,0,1]
	v_mul_f32_e32 v16, v23, v23
	v_mul_f32_e32 v17, v25, v25
	v_pk_fma_f32 v[18:19], v[18:19], 0.5, v[32:33] op_sel_hi:[1,0,1]
	v_mul_f32_e32 v32, v31, v31
	v_fmac_f32_e32 v16, v22, v22
	v_fmac_f32_e32 v17, v24, v24
	v_mul_f32_e32 v33, v19, v19
	v_fmac_f32_e32 v32, v30, v30
	v_add_f32_e32 v16, v16, v17
	v_add_f32_e32 v16, v32, v16
	v_fmac_f32_e32 v33, v18, v18
	v_add_f32_e32 v16, v33, v16
	v_add_f32_e32 v16, v42, v16
	ds_bpermute_b32 v17, v164, v16
	v_cvt_pk_bf16_f32 v22, v22, v23
	v_cvt_pk_bf16_f32 v23, v24, v25
	v_cvt_pk_bf16_f32 v24, v30, v31
	v_cvt_pk_bf16_f32 v25, v18, v19
	s_waitcnt lgkmcnt(0)
	v_add_f32_e32 v16, v16, v17
	ds_bpermute_b32 v17, v165, v16
	global_store_dwordx4 v[40:41], v[22:25], off offset:256
	s_and_saveexec_b64 s[26:27], s[38:39]
	s_cbranch_execz .LBB0_2083
	v_lshlrev_b64 v[18:19], 6, v[34:35]
	v_lshl_add_u64 v[18:19], s[78:79], 0, v[18:19]
	v_lshl_add_u64 v[18:19], s[14:15], 2, v[18:19]
	s_lshl_b32 s24, s47, 2
	v_lshl_add_u64 v[18:19], v[18:19], 0, s[24:25]
	s_waitcnt lgkmcnt(0)
	v_add_f32_e32 v16, v16, v17
	global_store_dword v[18:19], v16, off
.LBB0_2083:
	s_or_b64 exec, exec, s[26:27]
	v_add_u32_e32 v16, 0xb0, v146
	s_waitcnt lgkmcnt(0)
	v_ashrrev_i32_e32 v17, 31, v16
	v_lshlrev_b64 v[18:19], 11, v[16:17]
	v_lshl_add_u64 v[18:19], s[18:19], 0, v[18:19]
	v_lshl_add_u64 v[18:19], v[144:145], 1, v[18:19]
	v_mov_b32_e32 v22, v244
	v_mov_b32_e32 v23, v245
	v_mov_b32_e32 v24, v246
	v_mov_b32_e32 v25, v247
	v_lshlrev_b32_e32 v26, 16, v22
	v_and_b32_e32 v27, 0xffff0000, v22
	v_lshlrev_b32_e32 v22, 16, v23
	v_and_b32_e32 v23, 0xffff0000, v23
	v_lshlrev_b32_e32 v28, 16, v24
	v_and_b32_e32 v29, 0xffff0000, v24
	v_lshlrev_b32_e32 v24, 16, v25
	v_and_b32_e32 v25, 0xffff0000, v25
	v_pk_fma_f32 v[22:23], v[14:15], 0.5, v[22:23] op_sel_hi:[1,0,1]
	v_pk_fma_f32 v[26:27], v[12:13], 0.5, v[26:27] op_sel_hi:[1,0,1]
	v_pk_fma_f32 v[24:25], v[10:11], 0.5, v[24:25] op_sel_hi:[1,0,1]
	v_pk_fma_f32 v[28:29], v[8:9], 0.5, v[28:29] op_sel_hi:[1,0,1]
	v_cvt_pk_bf16_f32 v8, v26, v27
	v_cvt_pk_bf16_f32 v9, v22, v23
	v_mul_f32_e32 v27, v27, v27
	v_cvt_pk_bf16_f32 v10, v28, v29
	v_cvt_pk_bf16_f32 v11, v24, v25
	v_mov_b32_e32 v12, v248
	v_mov_b32_e32 v13, v249
	v_mov_b32_e32 v14, v250
	v_mov_b32_e32 v15, v251
	v_mul_f32_e32 v23, v23, v23
	v_mul_f32_e32 v29, v29, v29
	v_fmac_f32_e32 v27, v26, v26
	v_fmac_f32_e32 v23, v22, v22
	v_mul_f32_e32 v25, v25, v25
	v_fmac_f32_e32 v29, v28, v28
	v_add_f32_e32 v22, v27, v23
	v_fmac_f32_e32 v25, v24, v24
	v_add_f32_e32 v22, v29, v22
	v_add_f32_e32 v26, v25, v22
	global_store_dwordx4 v[18:19], v[8:11], off
	v_lshlrev_b32_e32 v22, 16, v12
	v_and_b32_e32 v23, 0xffff0000, v12
	v_lshlrev_b32_e32 v12, 16, v13
	v_and_b32_e32 v13, 0xffff0000, v13
	v_lshlrev_b32_e32 v24, 16, v14
	v_and_b32_e32 v25, 0xffff0000, v14
	v_lshlrev_b32_e32 v14, 16, v15
	v_and_b32_e32 v15, 0xffff0000, v15
	v_pk_fma_f32 v[6:7], v[6:7], 0.5, v[12:13] op_sel_hi:[1,0,1]
	v_pk_fma_f32 v[4:5], v[4:5], 0.5, v[22:23] op_sel_hi:[1,0,1]
	v_pk_fma_f32 v[12:13], v[2:3], 0.5, v[14:15] op_sel_hi:[1,0,1]
	v_pk_fma_f32 v[14:15], v[0:1], 0.5, v[24:25] op_sel_hi:[1,0,1]
	v_mul_f32_e32 v0, v5, v5
	v_mul_f32_e32 v1, v7, v7
	v_mul_f32_e32 v2, v15, v15
	v_fmac_f32_e32 v0, v4, v4
	v_fmac_f32_e32 v1, v6, v6
	v_mul_f32_e32 v3, v13, v13
	v_fmac_f32_e32 v2, v14, v14
	v_add_f32_e32 v0, v0, v1
	v_add_f32_e32 v0, v2, v0
	v_fmac_f32_e32 v3, v12, v12
	v_add_f32_e32 v0, v3, v0
	v_add_f32_e32 v0, v26, v0
	ds_bpermute_b32 v1, v164, v0
	v_cvt_pk_bf16_f32 v2, v4, v5
	v_cvt_pk_bf16_f32 v3, v6, v7
	v_cvt_pk_bf16_f32 v4, v14, v15
	v_cvt_pk_bf16_f32 v5, v12, v13
	s_waitcnt lgkmcnt(0)
	v_add_f32_e32 v0, v0, v1
	ds_bpermute_b32 v1, v165, v0
	global_store_dwordx4 v[18:19], v[2:5], off offset:256
	s_and_saveexec_b64 s[26:27], s[38:39]
	s_cbranch_execz .LBB0_2085
	v_lshlrev_b64 v[2:3], 6, v[16:17]
	v_lshl_add_u64 v[2:3], s[78:79], 0, v[2:3]
	v_lshl_add_u64 v[2:3], s[14:15], 2, v[2:3]
	s_lshl_b32 s24, s47, 2
	v_lshl_add_u64 v[2:3], v[2:3], 0, s[24:25]
	s_waitcnt lgkmcnt(0)
	v_add_f32_e32 v0, v0, v1
	global_store_dword v[2:3], v0, off
